# GEMM phases: dropped the full VMEM drain at tile boundaries
# baseline (speedup 1.0000x reference)
; template <class Epi>
; __device__ __forceinline__ void gemm_phase(LAS unsigned char* lds, const Gemm g, const StaticOrder& S, const Epi& E) {
;     ...
;     const bool has_next = S.next(ui + 1, nxt);
;     const char* nA = has_next ? (const char*)g.A + (size_t)nxt.pm * tstep : cA; const char* nB = has_next ? (const char*)g.Bt + (size_t)nxt.pn * tstep : cB;
;     ...
; #pragma unroll
;     for (int a = 0; a < 2; ++a)
; #pragma unroll
;       for (int b = 0; b < 2; ++b)
; #pragma unroll
;         for (int m = 0; m < 4; ++m)
; #pragma unroll
;           for (int n = 0; n < 2; ++n) acc[a][b][m][n] = (f32x4){0.f, 0.f, 0.f, 0.f};
;     cur = nxt; cA = nA; cB = nB; ++ui;
.LBB0_401:
	s_ashr_i32 s17, s16, 31
	v_cmp_lt_i64_e32 vcc, s[18:19], v[202:203]
	s_lshl_b64 s[18:19], s[16:17], 19
	s_add_u32 s18, s56, s18
	s_addc_u32 s19, s57, s19
	s_and_b64 s[20:21], vcc, exec
	s_cselect_b32 s17, s19, s27
	s_cselect_b32 s23, s18, s26
	s_ashr_i32 s11, s10, 31
	s_lshl_b64 s[20:21], s[10:11], 19
	s_add_u32 s20, s88, s20
	s_addc_u32 s21, s89, s21
	s_and_b64 s[34:35], vcc, exec
	s_cselect_b32 s11, s21, s39
	s_cselect_b32 s76, s20, s38
	s_add_u32 s26, s26, 0x40080
	s_addc_u32 s27, s27, 0
	s_add_u32 s77, s38, 0x100
	v_mov_b32_e32 v16, 0
	s_addc_u32 s78, s39, 0
	s_mov_b32 s34, -2
	s_waitcnt lgkmcnt(0)
	v_mov_b32_e32 v17, v16
	v_mov_b32_e32 v18, v16
	v_mov_b32_e32 v19, v16
	v_mov_b32_e32 v20, v16
	v_mov_b32_e32 v21, v16
	v_mov_b32_e32 v22, v16
	v_mov_b32_e32 v23, v16
	s_nop 0
	v_mov_b32_e32 v32, v16
	v_mov_b32_e32 v33, v16
	v_mov_b32_e32 v34, v16
	v_mov_b32_e32 v35, v16
	v_mov_b32_e32 v36, v16
	v_mov_b32_e32 v37, v16
	v_mov_b32_e32 v38, v16
	v_mov_b32_e32 v39, v16
	v_mov_b32_e32 v48, v16
	v_mov_b32_e32 v49, v16
	v_mov_b32_e32 v50, v16
	v_mov_b32_e32 v51, v16
	v_mov_b32_e32 v52, v16
	v_mov_b32_e32 v53, v16
	v_mov_b32_e32 v54, v16
	v_mov_b32_e32 v55, v16
	v_mov_b32_e32 v64, v16
	v_mov_b32_e32 v65, v16
	v_mov_b32_e32 v66, v16
	v_mov_b32_e32 v67, v16
	v_mov_b32_e32 v68, v16
	v_mov_b32_e32 v69, v16
	v_mov_b32_e32 v70, v16
	v_mov_b32_e32 v71, v16
	v_mov_b32_e32 v24, v16
	v_mov_b32_e32 v25, v16
	v_mov_b32_e32 v26, v16
	v_mov_b32_e32 v27, v16
	v_mov_b32_e32 v28, v16
	v_mov_b32_e32 v29, v16
	v_mov_b32_e32 v30, v16
	v_mov_b32_e32 v31, v16
	v_mov_b32_e32 v40, v16
	v_mov_b32_e32 v41, v16
	v_mov_b32_e32 v42, v16
	v_mov_b32_e32 v43, v16
	v_mov_b32_e32 v44, v16
	v_mov_b32_e32 v45, v16
	v_mov_b32_e32 v46, v16
	v_mov_b32_e32 v47, v16
	v_mov_b32_e32 v56, v16
	v_mov_b32_e32 v57, v16
	v_mov_b32_e32 v58, v16
	v_mov_b32_e32 v59, v16
	v_mov_b32_e32 v60, v16
	v_mov_b32_e32 v61, v16
	v_mov_b32_e32 v62, v16
	v_mov_b32_e32 v63, v16
	v_mov_b32_e32 v72, v16
	v_mov_b32_e32 v73, v16
	v_mov_b32_e32 v74, v16
	v_mov_b32_e32 v75, v16
	v_mov_b32_e32 v76, v16
	v_mov_b32_e32 v77, v16
	v_mov_b32_e32 v78, v16
	v_mov_b32_e32 v79, v16
	v_mov_b32_e32 v80, v16
	v_mov_b32_e32 v81, v16
	v_mov_b32_e32 v82, v16
	v_mov_b32_e32 v83, v16
	v_mov_b32_e32 v84, v16
	v_mov_b32_e32 v85, v16
	v_mov_b32_e32 v86, v16
	v_mov_b32_e32 v87, v16
	v_mov_b32_e32 v96, v16
	v_mov_b32_e32 v97, v16
	v_mov_b32_e32 v98, v16
	v_mov_b32_e32 v99, v16
	v_mov_b32_e32 v100, v16
	v_mov_b32_e32 v101, v16
	v_mov_b32_e32 v102, v16
	v_mov_b32_e32 v103, v16
	v_mov_b32_e32 v112, v16
	v_mov_b32_e32 v113, v16
	v_mov_b32_e32 v114, v16
	v_mov_b32_e32 v115, v16
	v_mov_b32_e32 v116, v16
	v_mov_b32_e32 v117, v16
	v_mov_b32_e32 v118, v16
	v_mov_b32_e32 v119, v16
	v_mov_b32_e32 v128, v16
	v_mov_b32_e32 v129, v16
	v_mov_b32_e32 v130, v16
	v_mov_b32_e32 v131, v16
	v_mov_b32_e32 v132, v16
	v_mov_b32_e32 v133, v16
	v_mov_b32_e32 v134, v16
	v_mov_b32_e32 v135, v16
	v_mov_b32_e32 v88, v16
	v_mov_b32_e32 v89, v16
	v_mov_b32_e32 v90, v16
	v_mov_b32_e32 v91, v16
	v_mov_b32_e32 v92, v16
	v_mov_b32_e32 v93, v16
	v_mov_b32_e32 v94, v16
	v_mov_b32_e32 v95, v16
	v_mov_b32_e32 v104, v16
	v_mov_b32_e32 v105, v16
	v_mov_b32_e32 v106, v16
	v_mov_b32_e32 v107, v16
	v_mov_b32_e32 v108, v16
	v_mov_b32_e32 v109, v16
	v_mov_b32_e32 v110, v16
	v_mov_b32_e32 v111, v16
	v_mov_b32_e32 v120, v16
	v_mov_b32_e32 v121, v16
	v_mov_b32_e32 v122, v16
	v_mov_b32_e32 v123, v16
	v_mov_b32_e32 v124, v16
	v_mov_b32_e32 v125, v16
	v_mov_b32_e32 v126, v16
	v_mov_b32_e32 v127, v16
	v_mov_b32_e32 v136, v16
	v_mov_b32_e32 v137, v16
	v_mov_b32_e32 v138, v16
	v_mov_b32_e32 v139, v16
	v_mov_b32_e32 v140, v16
	v_mov_b32_e32 v141, v16
	v_mov_b32_e32 v142, v16
	v_mov_b32_e32 v143, v16

; template <class Epi>
; __device__ __forceinline__ void gemm_phase(LAS unsigned char* lds, const Gemm g, const StaticOrder& S, const Epi& E) {
;     ...
;     const bool has_next = S.next(ui + 1, nxt);
;     const char* nA = has_next ? (const char*)g.A + (size_t)nxt.pm * tstep : cA; const char* nB = has_next ? (const char*)g.Bt + (size_t)nxt.pn * tstep : cB;
;     ...
; #pragma unroll
;     for (int a = 0; a < 2; ++a)
; #pragma unroll
;       for (int b = 0; b < 2; ++b)
; #pragma unroll
;         for (int m = 0; m < 4; ++m)
; #pragma unroll
;           for (int n = 0; n < 2; ++n) acc[a][b][m][n] = (f32x4){0.f, 0.f, 0.f, 0.f};
;     cur = nxt; cA = nA; cB = nB; ++ui;
.LBB0_480:
	s_ashr_i32 s49, s48, 31
	s_lshl_b64 s[34:35], s[48:49], 19
	v_cmp_lt_i64_e32 vcc, s[50:51], v[184:185]
	s_add_u32 s50, s54, s34
	s_addc_u32 s51, s55, s35
	s_and_b64 s[34:35], vcc, exec
	s_cselect_b32 s39, s51, s61
	s_cselect_b32 s49, s50, s60
	s_ashr_i32 s47, s46, 31
	s_lshl_b64 s[34:35], s[46:47], 19
	v_readlane_b32 s12, v253, 18
	v_readlane_b32 s13, v253, 19
	s_add_u32 s58, s12, s34
	s_addc_u32 s59, s13, s35
	s_and_b64 s[34:35], vcc, exec
	s_cselect_b32 s47, s59, s67
	s_cselect_b32 vcc_lo, s58, s66
	s_add_u32 s60, s60, 0x40080
	s_addc_u32 s61, s61, 0
	s_add_u32 vcc_hi, s66, 0x100
	s_nop 0
	v_mov_b32_e32 v32, 0
	s_addc_u32 s34, s67, 0
	s_mov_b32 s35, -2
	v_mov_b32_e32 v33, v32
	v_mov_b32_e32 v34, v32
	v_mov_b32_e32 v35, v32
	v_mov_b32_e32 v64, v32
	v_mov_b32_e32 v65, v32
	v_mov_b32_e32 v66, v32
	v_mov_b32_e32 v67, v32
	v_mov_b32_e32 v20, v32
	v_mov_b32_e32 v21, v32
	v_mov_b32_e32 v22, v32
	v_mov_b32_e32 v23, v32
	v_mov_b32_e32 v48, v32
	v_mov_b32_e32 v49, v32
	v_mov_b32_e32 v50, v32
	v_mov_b32_e32 v51, v32
	v_mov_b32_e32 v16, v32
	v_mov_b32_e32 v17, v32
	v_mov_b32_e32 v18, v32
	v_mov_b32_e32 v19, v32
	v_mov_b32_e32 v52, v32
	v_mov_b32_e32 v53, v32
	v_mov_b32_e32 v54, v32
	v_mov_b32_e32 v55, v32
	v_mov_b32_e32 v40, v32
	v_mov_b32_e32 v41, v32
	v_mov_b32_e32 v42, v32
	v_mov_b32_e32 v43, v32
	v_mov_b32_e32 v72, v32
	v_mov_b32_e32 v73, v32
	v_mov_b32_e32 v74, v32
	v_mov_b32_e32 v75, v32
	v_mov_b32_e32 v36, v32
	v_mov_b32_e32 v37, v32
	v_mov_b32_e32 v38, v32
	v_mov_b32_e32 v39, v32
	v_mov_b32_e32 v68, v32
	v_mov_b32_e32 v69, v32
	v_mov_b32_e32 v70, v32
	v_mov_b32_e32 v71, v32
	v_mov_b32_e32 v28, v32
	v_mov_b32_e32 v29, v32
	v_mov_b32_e32 v30, v32
	v_mov_b32_e32 v31, v32
	v_mov_b32_e32 v56, v32
	v_mov_b32_e32 v57, v32
	v_mov_b32_e32 v58, v32
	v_mov_b32_e32 v59, v32
	v_mov_b32_e32 v24, v32
	v_mov_b32_e32 v25, v32
	v_mov_b32_e32 v26, v32
	v_mov_b32_e32 v27, v32
	v_mov_b32_e32 v60, v32
	v_mov_b32_e32 v61, v32
	v_mov_b32_e32 v62, v32
	v_mov_b32_e32 v63, v32
	v_mov_b32_e32 v44, v32
	v_mov_b32_e32 v45, v32
	v_mov_b32_e32 v46, v32
	v_mov_b32_e32 v47, v32
	v_mov_b32_e32 v76, v32
	v_mov_b32_e32 v77, v32
	v_mov_b32_e32 v78, v32
	v_mov_b32_e32 v79, v32
	v_mov_b32_e32 v96, v32
	v_mov_b32_e32 v97, v32
	v_mov_b32_e32 v98, v32
	v_mov_b32_e32 v99, v32
	v_mov_b32_e32 v160, v32
	v_mov_b32_e32 v161, v32
	v_mov_b32_e32 v162, v32
	v_mov_b32_e32 v163, v32
	v_mov_b32_e32 v80, v32
	v_mov_b32_e32 v81, v32
	v_mov_b32_e32 v82, v32
	v_mov_b32_e32 v83, v32
	v_mov_b32_e32 v112, v32
	v_mov_b32_e32 v113, v32
	v_mov_b32_e32 v114, v32
	v_mov_b32_e32 v115, v32
	v_mov_b32_e32 v84, v32
	v_mov_b32_e32 v85, v32
	v_mov_b32_e32 v86, v32
	v_mov_b32_e32 v87, v32
	v_mov_b32_e32 v116, v32
	v_mov_b32_e32 v117, v32
	v_mov_b32_e32 v118, v32
	v_mov_b32_e32 v119, v32
	v_mov_b32_e32 v104, v32
	v_mov_b32_e32 v105, v32
	v_mov_b32_e32 v106, v32
	v_mov_b32_e32 v107, v32
	v_mov_b32_e32 v168, v32
	v_mov_b32_e32 v169, v32
	v_mov_b32_e32 v170, v32
	v_mov_b32_e32 v171, v32
	v_mov_b32_e32 v100, v32
	v_mov_b32_e32 v101, v32
	v_mov_b32_e32 v102, v32
	v_mov_b32_e32 v103, v32
	v_mov_b32_e32 v164, v32
	v_mov_b32_e32 v165, v32
	v_mov_b32_e32 v166, v32
	v_mov_b32_e32 v167, v32
	v_mov_b32_e32 v88, v32
	v_mov_b32_e32 v89, v32
	v_mov_b32_e32 v90, v32
	v_mov_b32_e32 v91, v32
	v_mov_b32_e32 v120, v32
	v_mov_b32_e32 v121, v32
	v_mov_b32_e32 v122, v32
	v_mov_b32_e32 v123, v32
	v_mov_b32_e32 v92, v32
	v_mov_b32_e32 v93, v32
	v_mov_b32_e32 v94, v32
	v_mov_b32_e32 v95, v32
	v_mov_b32_e32 v124, v32
	v_mov_b32_e32 v125, v32
	v_mov_b32_e32 v126, v32
	v_mov_b32_e32 v127, v32
	v_mov_b32_e32 v108, v32
	v_mov_b32_e32 v109, v32
	v_mov_b32_e32 v110, v32
	v_mov_b32_e32 v111, v32
	v_mov_b32_e32 v172, v32
	v_mov_b32_e32 v173, v32
	v_mov_b32_e32 v174, v32
	v_mov_b32_e32 v175, v32

; template <class Epi>
; __device__ __forceinline__ void gemm_phase(LAS unsigned char* lds, const Gemm g, const StaticOrder& S, const Epi& E) {
;     ...
;     const bool has_next = S.next(ui + 1, nxt);
;     const char* nA = has_next ? (const char*)g.A + (size_t)nxt.pm * tstep : cA; const char* nB = has_next ? (const char*)g.Bt + (size_t)nxt.pn * tstep : cB;
;     ...
; #pragma unroll
;     for (int a = 0; a < 2; ++a)
; #pragma unroll
;       for (int b = 0; b < 2; ++b)
; #pragma unroll
;         for (int m = 0; m < 4; ++m)
; #pragma unroll
;           for (int n = 0; n < 2; ++n) acc[a][b][m][n] = (f32x4){0.f, 0.f, 0.f, 0.f};
;     cur = nxt; cA = nA; cB = nB; ++ui;
.LBB0_628:
	s_add_u32 s18, s18, 0xb0080
	s_addc_u32 s19, s19, 0
	s_add_u32 s63, s20, 0x100
	v_mov_b32_e32 v16, 0
	s_addc_u32 s34, s21, 0
	s_mov_b32 s35, -2
	s_waitcnt lgkmcnt(0)
	v_mov_b32_e32 v17, v16
	v_mov_b32_e32 v18, v16
	v_mov_b32_e32 v19, v16
	v_mov_b32_e32 v20, v16
	v_mov_b32_e32 v21, v16
	v_mov_b32_e32 v22, v16
	v_mov_b32_e32 v23, v16
	s_nop 0
	v_mov_b32_e32 v32, v16
	v_mov_b32_e32 v33, v16
	v_mov_b32_e32 v34, v16
	v_mov_b32_e32 v35, v16
	v_mov_b32_e32 v36, v16
	v_mov_b32_e32 v37, v16
	v_mov_b32_e32 v38, v16
	v_mov_b32_e32 v39, v16
	v_mov_b32_e32 v48, v16
	v_mov_b32_e32 v49, v16
	v_mov_b32_e32 v50, v16
	v_mov_b32_e32 v51, v16
	v_mov_b32_e32 v52, v16
	v_mov_b32_e32 v53, v16
	v_mov_b32_e32 v54, v16
	v_mov_b32_e32 v55, v16
	v_mov_b32_e32 v64, v16
	v_mov_b32_e32 v65, v16
	v_mov_b32_e32 v66, v16
	v_mov_b32_e32 v67, v16
	v_mov_b32_e32 v68, v16
	v_mov_b32_e32 v69, v16
	v_mov_b32_e32 v70, v16
	v_mov_b32_e32 v71, v16
	v_mov_b32_e32 v24, v16
	v_mov_b32_e32 v25, v16
	v_mov_b32_e32 v26, v16
	v_mov_b32_e32 v27, v16
	v_mov_b32_e32 v28, v16
	v_mov_b32_e32 v29, v16
	v_mov_b32_e32 v30, v16
	v_mov_b32_e32 v31, v16
	v_mov_b32_e32 v40, v16
	v_mov_b32_e32 v41, v16
	v_mov_b32_e32 v42, v16
	v_mov_b32_e32 v43, v16
	v_mov_b32_e32 v44, v16
	v_mov_b32_e32 v45, v16
	v_mov_b32_e32 v46, v16
	v_mov_b32_e32 v47, v16
	v_mov_b32_e32 v56, v16
	v_mov_b32_e32 v57, v16
	v_mov_b32_e32 v58, v16
	v_mov_b32_e32 v59, v16
	v_mov_b32_e32 v60, v16
	v_mov_b32_e32 v61, v16
	v_mov_b32_e32 v62, v16
	v_mov_b32_e32 v63, v16
	v_mov_b32_e32 v72, v16
	v_mov_b32_e32 v73, v16
	v_mov_b32_e32 v74, v16
	v_mov_b32_e32 v75, v16
	v_mov_b32_e32 v76, v16
	v_mov_b32_e32 v77, v16
	v_mov_b32_e32 v78, v16
	v_mov_b32_e32 v79, v16
	v_mov_b32_e32 v80, v16
	v_mov_b32_e32 v81, v16
	v_mov_b32_e32 v82, v16
	v_mov_b32_e32 v83, v16
	v_mov_b32_e32 v84, v16
	v_mov_b32_e32 v85, v16
	v_mov_b32_e32 v86, v16
	v_mov_b32_e32 v87, v16
	v_mov_b32_e32 v96, v16
	v_mov_b32_e32 v97, v16
	v_mov_b32_e32 v98, v16
	v_mov_b32_e32 v99, v16
	v_mov_b32_e32 v100, v16
	v_mov_b32_e32 v101, v16
	v_mov_b32_e32 v102, v16
	v_mov_b32_e32 v103, v16
	v_mov_b32_e32 v112, v16
	v_mov_b32_e32 v113, v16
	v_mov_b32_e32 v114, v16
	v_mov_b32_e32 v115, v16
	v_mov_b32_e32 v116, v16
	v_mov_b32_e32 v117, v16
	v_mov_b32_e32 v118, v16
	v_mov_b32_e32 v119, v16
	v_mov_b32_e32 v128, v16
	v_mov_b32_e32 v129, v16
	v_mov_b32_e32 v130, v16
	v_mov_b32_e32 v131, v16
	v_mov_b32_e32 v132, v16
	v_mov_b32_e32 v133, v16
	v_mov_b32_e32 v134, v16
	v_mov_b32_e32 v135, v16
	v_mov_b32_e32 v88, v16
	v_mov_b32_e32 v89, v16
	v_mov_b32_e32 v90, v16
	v_mov_b32_e32 v91, v16
	v_mov_b32_e32 v92, v16
	v_mov_b32_e32 v93, v16
	v_mov_b32_e32 v94, v16
	v_mov_b32_e32 v95, v16
	v_mov_b32_e32 v104, v16
	v_mov_b32_e32 v105, v16
	v_mov_b32_e32 v106, v16
	v_mov_b32_e32 v107, v16
	v_mov_b32_e32 v108, v16
	v_mov_b32_e32 v109, v16
	v_mov_b32_e32 v110, v16
	v_mov_b32_e32 v111, v16
	v_mov_b32_e32 v120, v16
	v_mov_b32_e32 v121, v16
	v_mov_b32_e32 v122, v16
	v_mov_b32_e32 v123, v16
	v_mov_b32_e32 v124, v16
	v_mov_b32_e32 v125, v16
	v_mov_b32_e32 v126, v16
	v_mov_b32_e32 v127, v16
	v_mov_b32_e32 v136, v16
	v_mov_b32_e32 v137, v16
	v_mov_b32_e32 v138, v16
	v_mov_b32_e32 v139, v16
	v_mov_b32_e32 v140, v16
	v_mov_b32_e32 v141, v16
	v_mov_b32_e32 v142, v16
	v_mov_b32_e32 v143, v16

; template <class Epi>
; __device__ __forceinline__ void gemm_phase(LAS unsigned char* lds, const Gemm g, const StaticOrder& S, const Epi& E) {
;     ...
;     const bool has_next = S.next(ui + 1, nxt);
;     const char* nA = has_next ? (const char*)g.A + (size_t)nxt.pm * tstep : cA; const char* nB = has_next ? (const char*)g.Bt + (size_t)nxt.pn * tstep : cB;
;     ...
; #pragma unroll
;     for (int a = 0; a < 2; ++a)
; #pragma unroll
;       for (int b = 0; b < 2; ++b)
; #pragma unroll
;         for (int m = 0; m < 4; ++m)
; #pragma unroll
;           for (int n = 0; n < 2; ++n) acc[a][b][m][n] = (f32x4){0.f, 0.f, 0.f, 0.f};
;     cur = nxt; cA = nA; cB = nB; ++ui;
.LBB0_711:
	s_ashr_i32 s45, s44, 31
	s_lshl_b64 s[34:35], s[44:45], 19
	s_add_u32 s50, s54, s34
	v_cmp_lt_i64_e32 vcc, s[38:39], v[170:171]
	s_addc_u32 s51, s55, s35
	s_and_b64 s[34:35], vcc, exec
	s_cselect_b32 s7, s51, s9
	s_cselect_b32 s18, s50, s8
	s_ashr_i32 s27, s26, 31
	s_lshl_b64 s[34:35], s[26:27], 19
	s_add_u32 s58, s42, s34
	s_addc_u32 s59, s43, s35
	s_and_b64 s[34:35], vcc, exec
	s_cselect_b32 s27, s59, s11
	s_cselect_b32 s40, s58, s10
	s_add_u32 s8, s8, 0x40080
	s_addc_u32 s9, s9, 0
	s_add_u32 s41, s10, 0x100
	v_mov_b32_e32 v20, 0
	s_addc_u32 s34, s11, 0
	s_mov_b32 s35, -2
	v_mov_b32_e32 v21, v20
	v_mov_b32_e32 v22, v20
	v_mov_b32_e32 v23, v20
	v_mov_b32_e32 v24, v20
	v_mov_b32_e32 v25, v20
	v_mov_b32_e32 v26, v20
	v_mov_b32_e32 v27, v20
	v_mov_b32_e32 v36, v20
	v_mov_b32_e32 v37, v20
	v_mov_b32_e32 v38, v20
	v_mov_b32_e32 v39, v20
	v_mov_b32_e32 v40, v20
	v_mov_b32_e32 v41, v20
	v_mov_b32_e32 v42, v20
	v_mov_b32_e32 v43, v20
	v_mov_b32_e32 v52, v20
	v_mov_b32_e32 v53, v20
	v_mov_b32_e32 v54, v20
	v_mov_b32_e32 v55, v20
	v_mov_b32_e32 v56, v20
	v_mov_b32_e32 v57, v20
	v_mov_b32_e32 v58, v20
	v_mov_b32_e32 v59, v20
	v_mov_b32_e32 v68, v20
	v_mov_b32_e32 v69, v20
	v_mov_b32_e32 v70, v20
	v_mov_b32_e32 v71, v20
	v_mov_b32_e32 v72, v20
	v_mov_b32_e32 v73, v20
	v_mov_b32_e32 v74, v20
	v_mov_b32_e32 v75, v20
	s_nop 0
	v_mov_b32_e32 v28, v20
	v_mov_b32_e32 v29, v20
	v_mov_b32_e32 v30, v20
	v_mov_b32_e32 v31, v20
	v_mov_b32_e32 v32, v20
	v_mov_b32_e32 v33, v20
	v_mov_b32_e32 v34, v20
	v_mov_b32_e32 v35, v20
	v_mov_b32_e32 v44, v20
	v_mov_b32_e32 v45, v20
	v_mov_b32_e32 v46, v20
	v_mov_b32_e32 v47, v20
	v_mov_b32_e32 v48, v20
	v_mov_b32_e32 v49, v20
	v_mov_b32_e32 v50, v20
	v_mov_b32_e32 v51, v20
	v_mov_b32_e32 v60, v20
	v_mov_b32_e32 v61, v20
	v_mov_b32_e32 v62, v20
	v_mov_b32_e32 v63, v20
	v_mov_b32_e32 v64, v20
	v_mov_b32_e32 v65, v20
	v_mov_b32_e32 v66, v20
	v_mov_b32_e32 v67, v20
	v_mov_b32_e32 v76, v20
	v_mov_b32_e32 v77, v20
	v_mov_b32_e32 v78, v20
	v_mov_b32_e32 v79, v20
	v_mov_b32_e32 v80, v20
	v_mov_b32_e32 v81, v20
	v_mov_b32_e32 v82, v20
	v_mov_b32_e32 v83, v20
	v_mov_b32_e32 v84, v20
	v_mov_b32_e32 v85, v20
	v_mov_b32_e32 v86, v20
	v_mov_b32_e32 v87, v20
	v_mov_b32_e32 v88, v20
	v_mov_b32_e32 v89, v20
	v_mov_b32_e32 v90, v20
	v_mov_b32_e32 v91, v20
	v_mov_b32_e32 v100, v20
	v_mov_b32_e32 v101, v20
	v_mov_b32_e32 v102, v20
	v_mov_b32_e32 v103, v20
	v_mov_b32_e32 v104, v20
	v_mov_b32_e32 v105, v20
	v_mov_b32_e32 v106, v20
	v_mov_b32_e32 v107, v20
	v_mov_b32_e32 v116, v20
	v_mov_b32_e32 v117, v20
	v_mov_b32_e32 v118, v20
	v_mov_b32_e32 v119, v20
	v_mov_b32_e32 v120, v20
	v_mov_b32_e32 v121, v20
	v_mov_b32_e32 v122, v20
	v_mov_b32_e32 v123, v20
	v_mov_b32_e32 v132, v20
	v_mov_b32_e32 v133, v20
	v_mov_b32_e32 v134, v20
	v_mov_b32_e32 v135, v20
	v_mov_b32_e32 v136, v20
	v_mov_b32_e32 v137, v20
	v_mov_b32_e32 v138, v20
	v_mov_b32_e32 v139, v20
	v_mov_b32_e32 v92, v20
	v_mov_b32_e32 v93, v20
	v_mov_b32_e32 v94, v20
	v_mov_b32_e32 v95, v20
	v_mov_b32_e32 v96, v20
	v_mov_b32_e32 v97, v20
	v_mov_b32_e32 v98, v20
	v_mov_b32_e32 v99, v20
	v_mov_b32_e32 v108, v20
	v_mov_b32_e32 v109, v20
	v_mov_b32_e32 v110, v20
	v_mov_b32_e32 v111, v20
	v_mov_b32_e32 v112, v20
	v_mov_b32_e32 v113, v20
	v_mov_b32_e32 v114, v20
	v_mov_b32_e32 v115, v20
	v_mov_b32_e32 v124, v20
	v_mov_b32_e32 v125, v20
	v_mov_b32_e32 v126, v20
	v_mov_b32_e32 v127, v20
	v_mov_b32_e32 v128, v20
	v_mov_b32_e32 v129, v20
	v_mov_b32_e32 v130, v20
	v_mov_b32_e32 v131, v20
	v_mov_b32_e32 v140, v20
	v_mov_b32_e32 v141, v20
	v_mov_b32_e32 v142, v20
	v_mov_b32_e32 v143, v20
	v_mov_b32_e32 v144, v20
	v_mov_b32_e32 v145, v20
	v_mov_b32_e32 v146, v20
	v_mov_b32_e32 v147, v20

; template <class Epi>
; __device__ __forceinline__ void gemm_phase(LAS unsigned char* lds, const Gemm g, const StaticOrder& S, const Epi& E) {
;     ...
;     const bool has_next = S.next(ui + 1, nxt);
;     const char* nA = has_next ? (const char*)g.A + (size_t)nxt.pm * tstep : cA; const char* nB = has_next ? (const char*)g.Bt + (size_t)nxt.pn * tstep : cB;
;     ...
; #pragma unroll
;     for (int a = 0; a < 2; ++a)
; #pragma unroll
;       for (int b = 0; b < 2; ++b)
; #pragma unroll
;         for (int m = 0; m < 4; ++m)
; #pragma unroll
;           for (int n = 0; n < 2; ++n) acc[a][b][m][n] = (f32x4){0.f, 0.f, 0.f, 0.f};
;     cur = nxt; cA = nA; cB = nB; ++ui;
.LBB0_1421:
	s_ashr_i32 s15, s14, 31
	v_cmp_lt_i64_e32 vcc, s[16:17], v[152:153]
	s_lshl_b64 s[16:17], s[14:15], 19
	s_add_u32 s16, s56, s16
	s_addc_u32 s17, s57, s17
	s_and_b64 s[18:19], vcc, exec
	s_cselect_b32 s15, s17, s25
	s_cselect_b32 s21, s16, s24
	s_ashr_i32 s13, s12, 31
	s_lshl_b64 s[18:19], s[12:13], 19
	s_add_u32 s18, s70, s18
	s_addc_u32 s19, s71, s19
	s_and_b64 s[28:29], vcc, exec
	s_cselect_b32 s13, s19, s27
	s_cselect_b32 s50, s18, s26
	s_add_u32 s24, s24, 0x40080
	s_addc_u32 s25, s25, 0
	s_add_u32 s51, s26, 0x100
	v_mov_b32_e32 v16, 0
	s_addc_u32 s58, s27, 0
	s_mov_b32 s59, -2
	s_waitcnt lgkmcnt(0)
	v_mov_b32_e32 v17, v16
	v_mov_b32_e32 v18, v16
	v_mov_b32_e32 v19, v16
	v_mov_b32_e32 v20, v16
	v_mov_b32_e32 v21, v16
	v_mov_b32_e32 v22, v16
	v_mov_b32_e32 v23, v16
	s_nop 0
	v_mov_b32_e32 v32, v16
	v_mov_b32_e32 v33, v16
	v_mov_b32_e32 v34, v16
	v_mov_b32_e32 v35, v16
	v_mov_b32_e32 v36, v16
	v_mov_b32_e32 v37, v16
	v_mov_b32_e32 v38, v16
	v_mov_b32_e32 v39, v16
	v_mov_b32_e32 v48, v16
	v_mov_b32_e32 v49, v16
	v_mov_b32_e32 v50, v16
	v_mov_b32_e32 v51, v16
	v_mov_b32_e32 v52, v16
	v_mov_b32_e32 v53, v16
	v_mov_b32_e32 v54, v16
	v_mov_b32_e32 v55, v16
	v_mov_b32_e32 v64, v16
	v_mov_b32_e32 v65, v16
	v_mov_b32_e32 v66, v16
	v_mov_b32_e32 v67, v16
	v_mov_b32_e32 v68, v16
	v_mov_b32_e32 v69, v16
	v_mov_b32_e32 v70, v16
	v_mov_b32_e32 v71, v16
	v_mov_b32_e32 v24, v16
	v_mov_b32_e32 v25, v16
	v_mov_b32_e32 v26, v16
	v_mov_b32_e32 v27, v16
	v_mov_b32_e32 v28, v16
	v_mov_b32_e32 v29, v16
	v_mov_b32_e32 v30, v16
	v_mov_b32_e32 v31, v16
	v_mov_b32_e32 v40, v16
	v_mov_b32_e32 v41, v16
	v_mov_b32_e32 v42, v16
	v_mov_b32_e32 v43, v16
	v_mov_b32_e32 v44, v16
	v_mov_b32_e32 v45, v16
	v_mov_b32_e32 v46, v16
	v_mov_b32_e32 v47, v16
	v_mov_b32_e32 v56, v16
	v_mov_b32_e32 v57, v16
	v_mov_b32_e32 v58, v16
	v_mov_b32_e32 v59, v16
	v_mov_b32_e32 v60, v16
	v_mov_b32_e32 v61, v16
	v_mov_b32_e32 v62, v16
	v_mov_b32_e32 v63, v16
	v_mov_b32_e32 v72, v16
	v_mov_b32_e32 v73, v16
	v_mov_b32_e32 v74, v16
	v_mov_b32_e32 v75, v16
	v_mov_b32_e32 v76, v16
	v_mov_b32_e32 v77, v16
	v_mov_b32_e32 v78, v16
	v_mov_b32_e32 v79, v16
	v_mov_b32_e32 v80, v16
	v_mov_b32_e32 v81, v16
	v_mov_b32_e32 v82, v16
	v_mov_b32_e32 v83, v16
	v_mov_b32_e32 v84, v16
	v_mov_b32_e32 v85, v16
	v_mov_b32_e32 v86, v16
	v_mov_b32_e32 v87, v16
	v_mov_b32_e32 v96, v16
	v_mov_b32_e32 v97, v16
	v_mov_b32_e32 v98, v16
	v_mov_b32_e32 v99, v16
	v_mov_b32_e32 v100, v16
	v_mov_b32_e32 v101, v16
	v_mov_b32_e32 v102, v16
	v_mov_b32_e32 v103, v16
	v_mov_b32_e32 v112, v16
	v_mov_b32_e32 v113, v16
	v_mov_b32_e32 v114, v16
	v_mov_b32_e32 v115, v16
	v_mov_b32_e32 v116, v16
	v_mov_b32_e32 v117, v16
	v_mov_b32_e32 v118, v16
	v_mov_b32_e32 v119, v16
	v_mov_b32_e32 v128, v16
	v_mov_b32_e32 v129, v16
	v_mov_b32_e32 v130, v16
	v_mov_b32_e32 v131, v16
	v_mov_b32_e32 v132, v16
	v_mov_b32_e32 v133, v16
	v_mov_b32_e32 v134, v16
	v_mov_b32_e32 v135, v16
	v_mov_b32_e32 v88, v16
	v_mov_b32_e32 v89, v16
	v_mov_b32_e32 v90, v16
	v_mov_b32_e32 v91, v16
	v_mov_b32_e32 v92, v16
	v_mov_b32_e32 v93, v16
	v_mov_b32_e32 v94, v16
	v_mov_b32_e32 v95, v16
	v_mov_b32_e32 v104, v16
	v_mov_b32_e32 v105, v16
	v_mov_b32_e32 v106, v16
	v_mov_b32_e32 v107, v16
	v_mov_b32_e32 v108, v16
	v_mov_b32_e32 v109, v16
	v_mov_b32_e32 v110, v16
	v_mov_b32_e32 v111, v16
	v_mov_b32_e32 v120, v16
	v_mov_b32_e32 v121, v16
	v_mov_b32_e32 v122, v16
	v_mov_b32_e32 v123, v16
	v_mov_b32_e32 v124, v16
	v_mov_b32_e32 v125, v16
	v_mov_b32_e32 v126, v16
	v_mov_b32_e32 v127, v16
	v_mov_b32_e32 v136, v16
	v_mov_b32_e32 v137, v16
	v_mov_b32_e32 v138, v16
	v_mov_b32_e32 v139, v16
	v_mov_b32_e32 v140, v16
	v_mov_b32_e32 v141, v16
	v_mov_b32_e32 v142, v16
	v_mov_b32_e32 v143, v16

; template <class Epi>
; __device__ __forceinline__ void gemm_phase(LAS unsigned char* lds, const Gemm g, const StaticOrder& S, const Epi& E) {
;     ...
;     const bool has_next = S.next(ui + 1, nxt);
;     const char* nA = has_next ? (const char*)g.A + (size_t)nxt.pm * tstep : cA; const char* nB = has_next ? (const char*)g.Bt + (size_t)nxt.pn * tstep : cB;
;     ...
; #pragma unroll
;     for (int a = 0; a < 2; ++a)
; #pragma unroll
;       for (int b = 0; b < 2; ++b)
; #pragma unroll
;         for (int m = 0; m < 4; ++m)
; #pragma unroll
;           for (int n = 0; n < 2; ++n) acc[a][b][m][n] = (f32x4){0.f, 0.f, 0.f, 0.f};
;     cur = nxt; cA = nA; cB = nB; ++ui;
.LBB0_1500:
	s_ashr_i32 s39, s38, 31
	v_cmp_lt_i64_e32 vcc, s[40:41], v[184:185]
	s_lshl_b64 s[40:41], s[38:39], 19
	s_add_u32 s40, s54, s40
	s_addc_u32 s41, s55, s41
	s_and_b64 s[42:43], vcc, exec
	s_cselect_b32 s13, s41, s47
	s_cselect_b32 s39, s40, s46
	s_ashr_i32 s37, s36, 31
	s_lshl_b64 s[42:43], s[36:37], 19
	s_add_u32 s42, s68, s42
	s_addc_u32 s43, s69, s43
	s_and_b64 s[50:51], vcc, exec
	s_cselect_b32 s37, s43, s49
	s_cselect_b32 s89, s42, s48
	s_add_u32 s46, s46, 0x40080
	s_addc_u32 s47, s47, 0
	s_add_u32 s90, s48, 0x100
	s_nop 0
	v_mov_b32_e32 v32, 0
	s_addc_u32 s91, s49, 0
	s_mov_b32 s92, -2
	v_mov_b32_e32 v33, v32
	v_mov_b32_e32 v34, v32
	v_mov_b32_e32 v35, v32
	v_mov_b32_e32 v64, v32
	v_mov_b32_e32 v65, v32
	v_mov_b32_e32 v66, v32
	v_mov_b32_e32 v67, v32
	v_mov_b32_e32 v20, v32
	v_mov_b32_e32 v21, v32
	v_mov_b32_e32 v22, v32
	v_mov_b32_e32 v23, v32
	v_mov_b32_e32 v48, v32
	v_mov_b32_e32 v49, v32
	v_mov_b32_e32 v50, v32
	v_mov_b32_e32 v51, v32
	v_mov_b32_e32 v16, v32
	v_mov_b32_e32 v17, v32
	v_mov_b32_e32 v18, v32
	v_mov_b32_e32 v19, v32
	v_mov_b32_e32 v52, v32
	v_mov_b32_e32 v53, v32
	v_mov_b32_e32 v54, v32
	v_mov_b32_e32 v55, v32
	v_mov_b32_e32 v40, v32
	v_mov_b32_e32 v41, v32
	v_mov_b32_e32 v42, v32
	v_mov_b32_e32 v43, v32
	v_mov_b32_e32 v72, v32
	v_mov_b32_e32 v73, v32
	v_mov_b32_e32 v74, v32
	v_mov_b32_e32 v75, v32
	v_mov_b32_e32 v36, v32
	v_mov_b32_e32 v37, v32
	v_mov_b32_e32 v38, v32
	v_mov_b32_e32 v39, v32
	v_mov_b32_e32 v68, v32
	v_mov_b32_e32 v69, v32
	v_mov_b32_e32 v70, v32
	v_mov_b32_e32 v71, v32
	v_mov_b32_e32 v28, v32
	v_mov_b32_e32 v29, v32
	v_mov_b32_e32 v30, v32
	v_mov_b32_e32 v31, v32
	v_mov_b32_e32 v56, v32
	v_mov_b32_e32 v57, v32
	v_mov_b32_e32 v58, v32
	v_mov_b32_e32 v59, v32
	v_mov_b32_e32 v24, v32
	v_mov_b32_e32 v25, v32
	v_mov_b32_e32 v26, v32
	v_mov_b32_e32 v27, v32
	v_mov_b32_e32 v60, v32
	v_mov_b32_e32 v61, v32
	v_mov_b32_e32 v62, v32
	v_mov_b32_e32 v63, v32
	v_mov_b32_e32 v44, v32
	v_mov_b32_e32 v45, v32
	v_mov_b32_e32 v46, v32
	v_mov_b32_e32 v47, v32
	v_mov_b32_e32 v76, v32
	v_mov_b32_e32 v77, v32
	v_mov_b32_e32 v78, v32
	v_mov_b32_e32 v79, v32
	v_mov_b32_e32 v96, v32
	v_mov_b32_e32 v97, v32
	v_mov_b32_e32 v98, v32
	v_mov_b32_e32 v99, v32
	v_mov_b32_e32 v140, v32
	v_mov_b32_e32 v141, v32
	v_mov_b32_e32 v142, v32
	v_mov_b32_e32 v143, v32
	v_mov_b32_e32 v80, v32
	v_mov_b32_e32 v81, v32
	v_mov_b32_e32 v82, v32
	v_mov_b32_e32 v83, v32
	v_mov_b32_e32 v112, v32
	v_mov_b32_e32 v113, v32
	v_mov_b32_e32 v114, v32
	v_mov_b32_e32 v115, v32
	v_mov_b32_e32 v84, v32
	v_mov_b32_e32 v85, v32
	v_mov_b32_e32 v86, v32
	v_mov_b32_e32 v87, v32
	v_mov_b32_e32 v116, v32
	v_mov_b32_e32 v117, v32
	v_mov_b32_e32 v118, v32
	v_mov_b32_e32 v119, v32
	v_mov_b32_e32 v104, v32
	v_mov_b32_e32 v105, v32
	v_mov_b32_e32 v106, v32
	v_mov_b32_e32 v107, v32
	v_mov_b32_e32 v168, v32
	v_mov_b32_e32 v169, v32
	v_mov_b32_e32 v170, v32
	v_mov_b32_e32 v171, v32
	v_mov_b32_e32 v100, v32
	v_mov_b32_e32 v101, v32
	v_mov_b32_e32 v102, v32
	v_mov_b32_e32 v103, v32
	v_mov_b32_e32 v164, v32
	v_mov_b32_e32 v165, v32
	v_mov_b32_e32 v166, v32
	v_mov_b32_e32 v167, v32
	v_mov_b32_e32 v88, v32
	v_mov_b32_e32 v89, v32
	v_mov_b32_e32 v90, v32
	v_mov_b32_e32 v91, v32
	v_mov_b32_e32 v120, v32
	v_mov_b32_e32 v121, v32
	v_mov_b32_e32 v122, v32
	v_mov_b32_e32 v123, v32
	v_mov_b32_e32 v92, v32
	v_mov_b32_e32 v93, v32
	v_mov_b32_e32 v94, v32
	v_mov_b32_e32 v95, v32
	v_mov_b32_e32 v124, v32
	v_mov_b32_e32 v125, v32
	v_mov_b32_e32 v126, v32
	v_mov_b32_e32 v127, v32
	v_mov_b32_e32 v108, v32
	v_mov_b32_e32 v109, v32
	v_mov_b32_e32 v110, v32
	v_mov_b32_e32 v111, v32
	v_mov_b32_e32 v172, v32
	v_mov_b32_e32 v173, v32
	v_mov_b32_e32 v174, v32
	v_mov_b32_e32 v175, v32

; template <class Epi>
; __device__ __forceinline__ void gemm_phase(LAS unsigned char* lds, const Gemm g, const StaticOrder& S, const Epi& E) {
;     ...
;     const bool has_next = S.next(ui + 1, nxt);
;     const char* nA = has_next ? (const char*)g.A + (size_t)nxt.pm * tstep : cA; const char* nB = has_next ? (const char*)g.Bt + (size_t)nxt.pn * tstep : cB;
;     ...
; #pragma unroll
;     for (int a = 0; a < 2; ++a)
; #pragma unroll
;       for (int b = 0; b < 2; ++b)
; #pragma unroll
;         for (int m = 0; m < 4; ++m)
; #pragma unroll
;           for (int n = 0; n < 2; ++n) acc[a][b][m][n] = (f32x4){0.f, 0.f, 0.f, 0.f};
;     cur = nxt; cA = nA; cB = nB; ++ui;
.LBB0_1648:
	s_add_u32 s16, s16, 0xb0080
	s_addc_u32 s17, s17, 0
	s_add_u32 s47, s18, 0x100
	v_mov_b32_e32 v16, 0
	s_addc_u32 s48, s19, 0
	s_mov_b32 s49, -2
	s_waitcnt lgkmcnt(0)
	v_mov_b32_e32 v17, v16
	v_mov_b32_e32 v18, v16
	v_mov_b32_e32 v19, v16
	v_mov_b32_e32 v20, v16
	v_mov_b32_e32 v21, v16
	v_mov_b32_e32 v22, v16
	v_mov_b32_e32 v23, v16
	s_nop 0
	v_mov_b32_e32 v32, v16
	v_mov_b32_e32 v33, v16
	v_mov_b32_e32 v34, v16
	v_mov_b32_e32 v35, v16
	v_mov_b32_e32 v36, v16
	v_mov_b32_e32 v37, v16
	v_mov_b32_e32 v38, v16
	v_mov_b32_e32 v39, v16
	v_mov_b32_e32 v48, v16
	v_mov_b32_e32 v49, v16
	v_mov_b32_e32 v50, v16
	v_mov_b32_e32 v51, v16
	v_mov_b32_e32 v52, v16
	v_mov_b32_e32 v53, v16
	v_mov_b32_e32 v54, v16
	v_mov_b32_e32 v55, v16
	v_mov_b32_e32 v64, v16
	v_mov_b32_e32 v65, v16
	v_mov_b32_e32 v66, v16
	v_mov_b32_e32 v67, v16
	v_mov_b32_e32 v68, v16
	v_mov_b32_e32 v69, v16
	v_mov_b32_e32 v70, v16
	v_mov_b32_e32 v71, v16
	v_mov_b32_e32 v24, v16
	v_mov_b32_e32 v25, v16
	v_mov_b32_e32 v26, v16
	v_mov_b32_e32 v27, v16
	v_mov_b32_e32 v28, v16
	v_mov_b32_e32 v29, v16
	v_mov_b32_e32 v30, v16
	v_mov_b32_e32 v31, v16
	v_mov_b32_e32 v40, v16
	v_mov_b32_e32 v41, v16
	v_mov_b32_e32 v42, v16
	v_mov_b32_e32 v43, v16
	v_mov_b32_e32 v44, v16
	v_mov_b32_e32 v45, v16
	v_mov_b32_e32 v46, v16
	v_mov_b32_e32 v47, v16
	v_mov_b32_e32 v56, v16
	v_mov_b32_e32 v57, v16
	v_mov_b32_e32 v58, v16
	v_mov_b32_e32 v59, v16
	v_mov_b32_e32 v60, v16
	v_mov_b32_e32 v61, v16
	v_mov_b32_e32 v62, v16
	v_mov_b32_e32 v63, v16
	v_mov_b32_e32 v72, v16
	v_mov_b32_e32 v73, v16
	v_mov_b32_e32 v74, v16
	v_mov_b32_e32 v75, v16
	v_mov_b32_e32 v76, v16
	v_mov_b32_e32 v77, v16
	v_mov_b32_e32 v78, v16
	v_mov_b32_e32 v79, v16
	v_mov_b32_e32 v80, v16
	v_mov_b32_e32 v81, v16
	v_mov_b32_e32 v82, v16
	v_mov_b32_e32 v83, v16
	v_mov_b32_e32 v84, v16
	v_mov_b32_e32 v85, v16
	v_mov_b32_e32 v86, v16
	v_mov_b32_e32 v87, v16
	v_mov_b32_e32 v96, v16
	v_mov_b32_e32 v97, v16
	v_mov_b32_e32 v98, v16
	v_mov_b32_e32 v99, v16
	v_mov_b32_e32 v100, v16
	v_mov_b32_e32 v101, v16
	v_mov_b32_e32 v102, v16
	v_mov_b32_e32 v103, v16
	v_mov_b32_e32 v112, v16
	v_mov_b32_e32 v113, v16
	v_mov_b32_e32 v114, v16
	v_mov_b32_e32 v115, v16
	v_mov_b32_e32 v116, v16
	v_mov_b32_e32 v117, v16
	v_mov_b32_e32 v118, v16
	v_mov_b32_e32 v119, v16
	v_mov_b32_e32 v128, v16
	v_mov_b32_e32 v129, v16
	v_mov_b32_e32 v130, v16
	v_mov_b32_e32 v131, v16
	v_mov_b32_e32 v132, v16
	v_mov_b32_e32 v133, v16
	v_mov_b32_e32 v134, v16
	v_mov_b32_e32 v135, v16
	v_mov_b32_e32 v88, v16
	v_mov_b32_e32 v89, v16
	v_mov_b32_e32 v90, v16
	v_mov_b32_e32 v91, v16
	v_mov_b32_e32 v92, v16
	v_mov_b32_e32 v93, v16
	v_mov_b32_e32 v94, v16
	v_mov_b32_e32 v95, v16
	v_mov_b32_e32 v104, v16
	v_mov_b32_e32 v105, v16
	v_mov_b32_e32 v106, v16
	v_mov_b32_e32 v107, v16
	v_mov_b32_e32 v108, v16
	v_mov_b32_e32 v109, v16
	v_mov_b32_e32 v110, v16
	v_mov_b32_e32 v111, v16
	v_mov_b32_e32 v120, v16
	v_mov_b32_e32 v121, v16
	v_mov_b32_e32 v122, v16
	v_mov_b32_e32 v123, v16
	v_mov_b32_e32 v124, v16
	v_mov_b32_e32 v125, v16
	v_mov_b32_e32 v126, v16
	v_mov_b32_e32 v127, v16
	v_mov_b32_e32 v136, v16
	v_mov_b32_e32 v137, v16
	v_mov_b32_e32 v138, v16
	v_mov_b32_e32 v139, v16
	v_mov_b32_e32 v140, v16
	v_mov_b32_e32 v141, v16
	v_mov_b32_e32 v142, v16
	v_mov_b32_e32 v143, v16
